# P2 conv_pull: FFN2 gate/up weight items dealt as 4 k-block x 2 n-block patches per workgroup step (512 B contiguous reads and 512 B contiguous bf16 row writes instead of 2 KiB / 128 B); pure permutati
# speedup vs baseline: 1.0015x; 1.0009x over previous
.LBB0_217:
	s_cmpk_lg_u32 s34, 0x5600
	s_cbranch_scc1 .Lrm_skip_0
	s_lshr_b32 s98, s36, 6
	s_mul_i32 s99, s98, 0x5f5
	s_lshr_b32 s99, s99, 16
	s_mul_i32 s100, s99, 43
	s_sub_i32 s98, s98, s100
	s_lshl_b32 s99, s99, 3
	s_lshl_b32 s98, s98, 3
	s_bfe_u32 s100, s36, 0x20001
	s_add_i32 s99, s99, s100
	s_bfe_u32 s100, s36, 0x10003
	s_lshl_b32 s100, s100, 2
	s_add_i32 s99, s99, s100
	s_and_b32 s100, s36, 1
	s_add_i32 s98, s98, s100
	s_bfe_u32 s100, s36, 0x20004
	s_lshl_b32 s100, s100, 1
	s_add_i32 s98, s98, s100
	s_mul_i32 s99, s99, 0x158
	s_add_i32 s36, s99, s98

.LBB0_258:
	s_cmpk_lg_u32 s34, 0x5600
	s_cbranch_scc1 .Lrm_skip_1
	s_lshr_b32 s98, s38, 6
	s_mul_i32 s99, s98, 0x5f5
	s_lshr_b32 s99, s99, 16
	s_mul_i32 s100, s99, 43
	s_sub_i32 s98, s98, s100
	s_lshl_b32 s99, s99, 3
	s_lshl_b32 s98, s98, 3
	s_bfe_u32 s100, s38, 0x20001
	s_add_i32 s99, s99, s100
	s_bfe_u32 s100, s38, 0x10003
	s_lshl_b32 s100, s100, 2
	s_add_i32 s99, s99, s100
	s_and_b32 s100, s38, 1
	s_add_i32 s98, s98, s100
	s_bfe_u32 s100, s38, 0x20004
	s_lshl_b32 s100, s100, 1
	s_add_i32 s98, s98, s100
	s_mul_i32 s99, s99, 0x158
	s_add_i32 s38, s99, s98
